# v024 + attention loop heads: next-stage K/V load addresses formed by incrementing the running pointers first (no add_co/addc chains after the barrier) and wave-uniform tests kept scalar
# speedup vs baseline: 1.0205x; 1.0205x over previous
; #define LAS __attribute__((address_space(3)))
;     __device__ __forceinline__ bool skip(int t) const { const int nb = t >> 2; if (nb >= qb) return 64 * (t & 3) > wq0 + 31; return !__any((int)((sel >> nb) & 1u)); }
; template <bool HAS_POST, class MaskF>
; __device__ __forceinline__ void attn_run(LAS unsigned char* lds, const bf16* Kg, const bf16* Vg, int pitch, int t0, int t1,
;                                          const bf16x8 (&qr)[4], f32x16& o0, f32x16& o1, f32x16& o2, MaskF& mf, const int wv) {
;     ...
;     for (int ts = t0; ts < t1; ts += 2) {
;         const int cur = ((ts - t0) >> 1) & 1;
;         const bool more = (ts + 2 < t1), more2 = (ts + 3 < t1);
;         if (more) { kp += 2 * tstride; kreg0 = *(const v4u*)kp; vp += 2 * tstride; vreg0 = *(const v4u*)vp;
;             if (more2) { kreg1 = *(const v4u*)(kp + tstride); vreg1 = *(const v4u*)(vp + tstride); } }
; #pragma unroll
;         for (int j = 0; j < 2; ++j) {
;             const int t = ts + j;
;             if (t >= t1) break;
;             if (mf.skip(t)) continue;
;             f32x16 p0, p1; const f32x16 zc = {};
;             LAS unsigned char* Kb = lds + (cur * 2 + j) * KBUF + cx.kroff;
;             if (wv < 4) __builtin_amdgcn_s_setprio(1);
.LBB0_851:
	s_add_i32 s0, s16, -2
	s_cmp_lt_i32 s16, s34
	s_cselect_b64 s[14:15], -1, 0
	s_cmp_ge_i32 s16, s34
	s_cselect_b64 s[12:13], -1, 0
	s_cmp_lt_i32 s0, s22
	s_cselect_b64 s[4:5], -1, 0
	v_cndmask_b32_e64 v50, 0, 1, s[4:5]
	s_and_b64 vcc, exec, s[12:13]
	v_cmp_ne_u32_e64 s[6:7], 1, v50
	s_cbranch_vccnz .LBB0_855
	s_mov_b64 s[4:5], 0x4000
	v_lshl_add_u64 v[154:155], v[154:155], 0, s[4:5]
	v_lshl_add_u64 v[156:157], v[156:157], 0, s[4:5]
	global_load_dwordx4 v[82:85], v[154:155], off
	global_load_dwordx4 v[86:89], v[156:157], off
	s_and_b64 vcc, exec, s[6:7]
	s_cbranch_vccnz .LBB0_854
	s_mov_b64 s[4:5], 0x2000
	v_lshl_add_u64 v[50:51], v[154:155], 0, s[4:5]
	global_load_dwordx4 v[90:93], v[50:51], off
	v_lshl_add_u64 v[50:51], v[156:157], 0, s[4:5]
	global_load_dwordx4 v[94:97], v[50:51], off
.LBB0_854:
.LBB0_855:
	s_and_b32 s18, s0, 2
	s_cmp_ge_i32 s0, s34
	s_cbranch_scc1 .LBB0_874
	s_andn2_b64 s[8:9], exec, s[24:25]
	s_andn2_b64 vcc, exec, s[24:25]
	s_cbranch_vccnz .LBB0_858
	s_setprio 1

; #define LAS __attribute__((address_space(3)))
;     __device__ __forceinline__ bool skip(int t) const { const int nb = t >> 2; if (nb >= qb) return 64 * (t & 3) > wq0 + 31; return !__any((int)((sel >> nb) & 1u)); }
; template <bool HAS_POST, class MaskF>
; __device__ __forceinline__ void attn_run(LAS unsigned char* lds, const bf16* Kg, const bf16* Vg, int pitch, int t0, int t1,
;                                          const bf16x8 (&qr)[4], f32x16& o0, f32x16& o1, f32x16& o2, MaskF& mf, const int wv) {
;     ...
;     for (int ts = t0; ts < t1; ts += 2) {
;         const int cur = ((ts - t0) >> 1) & 1;
;         const bool more = (ts + 2 < t1), more2 = (ts + 3 < t1);
;         if (more) { kp += 2 * tstride; kreg0 = *(const v4u*)kp; vp += 2 * tstride; vreg0 = *(const v4u*)vp;
;             if (more2) { kreg1 = *(const v4u*)(kp + tstride); vreg1 = *(const v4u*)(vp + tstride); } }
; #pragma unroll
;         for (int j = 0; j < 2; ++j) {
;             const int t = ts + j;
;             if (t >= t1) break;
;             if (mf.skip(t)) continue;
;             f32x16 p0, p1; const f32x16 zc = {};
;             LAS unsigned char* Kb = lds + (cur * 2 + j) * KBUF + cx.kroff;
;             if (wv < 4) __builtin_amdgcn_s_setprio(1);
.LBB0_921:
	s_add_u32 s94, s4, 2
	s_addc_u32 s95, s5, 0
	s_cmp_gt_i32 s94, s38
	s_cselect_b64 s[20:21], -1, 0
	s_cmp_le_i32 s94, s38
	s_cselect_b64 s[96:97], -1, 0
	s_cmp_lt_i32 s4, s23
	s_cselect_b64 s[0:1], -1, 0
	v_cndmask_b32_e64 v50, 0, 1, s[0:1]
	s_and_b64 vcc, exec, s[20:21]
	v_cmp_ne_u32_e64 s[92:93], 1, v50
	s_cbranch_vccnz .LBB0_925
	s_mov_b64 s[0:1], 0xc0000
	v_lshl_add_u64 v[154:155], v[154:155], 0, s[0:1]
	v_lshl_add_u64 v[156:157], v[156:157], 0, s[0:1]
	global_load_dwordx4 v[82:85], v[154:155], off
	global_load_dwordx4 v[86:89], v[156:157], off
	s_and_b64 vcc, exec, s[92:93]
	s_cbranch_vccnz .LBB0_924
	s_mov_b64 s[0:1], 0x60000
	v_lshl_add_u64 v[50:51], v[154:155], 0, s[0:1]
	global_load_dwordx4 v[90:93], v[50:51], off
	v_lshl_add_u64 v[50:51], v[156:157], 0, s[0:1]
	global_load_dwordx4 v[94:97], v[50:51], off
.LBB0_924:
.LBB0_925:
	s_and_b32 s5, s4, 2
	s_cmp_gt_i32 s4, s38
	s_cbranch_scc1 .LBB0_944
	s_andn2_b64 s[18:19], exec, s[24:25]
	s_andn2_b64 vcc, exec, s[24:25]
	s_cbranch_vccnz .LBB0_928
	s_setprio 1

; #define LAS __attribute__((address_space(3)))
;     __device__ __forceinline__ bool skip(int t) const { const int nb = t >> 2; if (nb >= qb) return 64 * (t & 3) > wq0 + 31; return !__any((int)((sel >> nb) & 1u)); }
; template <bool HAS_POST, class MaskF>
; __device__ __forceinline__ void attn_run(LAS unsigned char* lds, const bf16* Kg, const bf16* Vg, int pitch, int t0, int t1,
;                                          const bf16x8 (&qr)[4], f32x16& o0, f32x16& o1, f32x16& o2, MaskF& mf, const int wv) {
;     ...
;     for (int ts = t0; ts < t1; ts += 2) {
;         const int cur = ((ts - t0) >> 1) & 1;
;         const bool more = (ts + 2 < t1), more2 = (ts + 3 < t1);
;         if (more) { kp += 2 * tstride; kreg0 = *(const v4u*)kp; vp += 2 * tstride; vreg0 = *(const v4u*)vp;
;             if (more2) { kreg1 = *(const v4u*)(kp + tstride); vreg1 = *(const v4u*)(vp + tstride); } }
; #pragma unroll
;         for (int j = 0; j < 2; ++j) {
;             const int t = ts + j;
;             if (t >= t1) break;
;             if (mf.skip(t)) continue;
;             f32x16 p0, p1; const f32x16 zc = {};
;             LAS unsigned char* Kb = lds + (cur * 2 + j) * KBUF + cx.kroff;
;             if (wv < 4) __builtin_amdgcn_s_setprio(1);
.LBB0_960:
	s_add_i32 s1, s3, s96
	s_add_i32 s0, s1, -8
	s_add_i32 s1, s1, -6
	s_cmp_le_i32 s1, s38
	s_cselect_b64 s[20:21], -1, 0
	s_cmp_lt_i32 s0, s23
	s_cselect_b64 s[4:5], -1, 0
	v_cndmask_b32_e64 v50, 0, 1, s[4:5]
	s_cmp_gt_i32 s1, s38
	v_cmp_ne_u32_e64 s[94:95], 1, v50
	s_cbranch_scc1 .LBB0_964
	s_mov_b64 s[4:5], 0xc0000
	v_lshl_add_u64 v[198:199], v[198:199], 0, s[4:5]
	v_lshl_add_u64 v[200:201], v[200:201], 0, s[4:5]
	global_load_dwordx4 v[132:135], v[198:199], off
	global_load_dwordx4 v[136:139], v[200:201], off
	s_and_b64 vcc, exec, s[94:95]
	s_cbranch_vccnz .LBB0_963
	s_mov_b64 s[4:5], 0x60000
	v_lshl_add_u64 v[50:51], v[198:199], 0, s[4:5]
	global_load_dwordx4 v[140:143], v[50:51], off
	v_lshl_add_u64 v[50:51], v[200:201], 0, s[4:5]
	global_load_dwordx4 v[144:147], v[50:51], off
.LBB0_963:
.LBB0_964:
	s_andn2_b64 s[18:19], exec, s[24:25]
	s_andn2_b64 vcc, exec, s[24:25]
	s_cbranch_vccnz .LBB0_966
	s_setprio 1

; #define LAS __attribute__((address_space(3)))
;     __device__ __forceinline__ bool skip(int t) const { const int nb = t >> 2; if (nb >= qb) return 64 * (t & 3) > wq0 + 31; return !__any((int)((sel >> nb) & 1u)); }
; template <bool HAS_POST, class MaskF>
; __device__ __forceinline__ void attn_run(LAS unsigned char* lds, const bf16* Kg, const bf16* Vg, int pitch, int t0, int t1,
;                                          const bf16x8 (&qr)[4], f32x16& o0, f32x16& o1, f32x16& o2, MaskF& mf, const int wv) {
;     ...
;     for (int ts = t0; ts < t1; ts += 2) {
;         const int cur = ((ts - t0) >> 1) & 1;
;         const bool more = (ts + 2 < t1), more2 = (ts + 3 < t1);
;         if (more) { kp += 2 * tstride; kreg0 = *(const v4u*)kp; vp += 2 * tstride; vreg0 = *(const v4u*)vp;
;             if (more2) { kreg1 = *(const v4u*)(kp + tstride); vreg1 = *(const v4u*)(vp + tstride); } }
; #pragma unroll
;         for (int j = 0; j < 2; ++j) {
;             const int t = ts + j;
;             if (t >= t1) break;
;             if (mf.skip(t)) continue;
;             f32x16 p0, p1; const f32x16 zc = {};
;             LAS unsigned char* Kb = lds + (cur * 2 + j) * KBUF + cx.kroff;
;             if (wv < 4) __builtin_amdgcn_s_setprio(1);
.LBB0_1007:
	s_add_i32 s0, s16, -2
	s_cmp_lt_i32 s16, s33
	s_cselect_b64 s[14:15], -1, 0
	s_cmp_ge_i32 s16, s33
	s_cselect_b64 s[12:13], -1, 0
	s_cmp_lt_i32 s0, s2
	s_cselect_b64 s[4:5], -1, 0
	v_cndmask_b32_e64 v50, 0, 1, s[4:5]
	s_and_b64 vcc, exec, s[12:13]
	v_cmp_ne_u32_e64 s[6:7], 1, v50
	s_cbranch_vccnz .LBB0_1011
	s_mov_b64 s[4:5], 0x4000
	v_lshl_add_u64 v[154:155], v[154:155], 0, s[4:5]
	v_lshl_add_u64 v[156:157], v[156:157], 0, s[4:5]
	global_load_dwordx4 v[82:85], v[154:155], off
	global_load_dwordx4 v[86:89], v[156:157], off
	s_and_b64 vcc, exec, s[6:7]
	s_cbranch_vccnz .LBB0_1010
	s_mov_b64 s[4:5], 0x2000
	v_lshl_add_u64 v[50:51], v[154:155], 0, s[4:5]
	global_load_dwordx4 v[90:93], v[50:51], off
	v_lshl_add_u64 v[50:51], v[156:157], 0, s[4:5]
	global_load_dwordx4 v[94:97], v[50:51], off
.LBB0_1010:
.LBB0_1011:
	s_and_b32 s18, s0, 2
	s_cmp_ge_i32 s0, s33
	s_cbranch_scc1 .LBB0_1030
	s_andn2_b64 s[8:9], exec, s[24:25]
	s_andn2_b64 vcc, exec, s[24:25]
	s_cbranch_vccnz .LBB0_1014
	s_setprio 1

; #define LAS __attribute__((address_space(3)))
;     __device__ __forceinline__ bool skip(int t) const { const int nb = t >> 2; if (nb >= qb) return 64 * (t & 3) > wq0 + 31; return !__any((int)((sel >> nb) & 1u)); }
; template <bool HAS_POST, class MaskF>
; __device__ __forceinline__ void attn_run(LAS unsigned char* lds, const bf16* Kg, const bf16* Vg, int pitch, int t0, int t1,
;                                          const bf16x8 (&qr)[4], f32x16& o0, f32x16& o1, f32x16& o2, MaskF& mf, const int wv) {
;     ...
;     for (int ts = t0; ts < t1; ts += 2) {
;         const int cur = ((ts - t0) >> 1) & 1;
;         const bool more = (ts + 2 < t1), more2 = (ts + 3 < t1);
;         if (more) { kp += 2 * tstride; kreg0 = *(const v4u*)kp; vp += 2 * tstride; vreg0 = *(const v4u*)vp;
;             if (more2) { kreg1 = *(const v4u*)(kp + tstride); vreg1 = *(const v4u*)(vp + tstride); } }
; #pragma unroll
;         for (int j = 0; j < 2; ++j) {
;             const int t = ts + j;
;             if (t >= t1) break;
;             if (mf.skip(t)) continue;
;             f32x16 p0, p1; const f32x16 zc = {};
;             LAS unsigned char* Kb = lds + (cur * 2 + j) * KBUF + cx.kroff;
;             if (wv < 4) __builtin_amdgcn_s_setprio(1);
.LBB0_1077:
	s_add_u32 s94, s4, 2
	s_addc_u32 s95, s5, 0
	s_cmp_gt_i32 s94, s39
	s_cselect_b64 s[20:21], -1, 0
	s_cmp_le_i32 s94, s39
	s_cselect_b64 s[96:97], -1, 0
	s_cmp_lt_i32 s4, s27
	s_cselect_b64 s[0:1], -1, 0
	v_cndmask_b32_e64 v50, 0, 1, s[0:1]
	s_and_b64 vcc, exec, s[20:21]
	v_cmp_ne_u32_e64 s[92:93], 1, v50
	s_cbranch_vccnz .LBB0_1081
	s_mov_b64 s[0:1], 0xc0000
	v_lshl_add_u64 v[154:155], v[154:155], 0, s[0:1]
	v_lshl_add_u64 v[156:157], v[156:157], 0, s[0:1]
	global_load_dwordx4 v[82:85], v[154:155], off
	global_load_dwordx4 v[86:89], v[156:157], off
	s_and_b64 vcc, exec, s[92:93]
	s_cbranch_vccnz .LBB0_1080
	s_mov_b64 s[0:1], 0x60000
	v_lshl_add_u64 v[50:51], v[154:155], 0, s[0:1]
	global_load_dwordx4 v[90:93], v[50:51], off
	v_lshl_add_u64 v[50:51], v[156:157], 0, s[0:1]
	global_load_dwordx4 v[94:97], v[50:51], off
.LBB0_1080:
.LBB0_1081:
	s_and_b32 s5, s4, 2
	s_cmp_gt_i32 s4, s39
	s_cbranch_scc1 .LBB0_1100
	s_andn2_b64 s[18:19], exec, s[24:25]
	s_andn2_b64 vcc, exec, s[24:25]
	s_cbranch_vccnz .LBB0_1084
	s_setprio 1

; template <bool HAS_POST, class MaskF>
; __device__ __forceinline__ void attn_run(LAS unsigned char* lds, const bf16* Kg, const bf16* Vg, int pitch, int t0, int t1,
;                                          const bf16x8 (&qr)[4], f32x16& o0, f32x16& o1, f32x16& o2, MaskF& mf, const int wv) {
;     ...
;     for (int ts = t0; ts < t1; ts += 2) {
;         const int cur = ((ts - t0) >> 1) & 1;
;         const bool more = (ts + 2 < t1), more2 = (ts + 3 < t1);
;         if (more) { kp += 2 * tstride; kreg0 = *(const v4u*)kp; vp += 2 * tstride; vreg0 = *(const v4u*)vp;
;             if (more2) { kreg1 = *(const v4u*)(kp + tstride); vreg1 = *(const v4u*)(vp + tstride); } }
.LBB0_1116:
	s_add_i32 s1, s35, s96
	s_add_i32 s0, s1, -8
	s_add_i32 s1, s1, -6
	s_cmp_le_i32 s1, s39
	s_cselect_b64 s[20:21], -1, 0
	s_cmp_lt_i32 s0, s27
	s_cselect_b64 s[4:5], -1, 0
	v_cndmask_b32_e64 v50, 0, 1, s[4:5]
	s_cmp_gt_i32 s1, s39
	v_cmp_ne_u32_e64 s[94:95], 1, v50
	s_cbranch_scc1 .LBB0_1120
	s_mov_b64 s[4:5], 0xc0000
	v_lshl_add_u64 v[198:199], v[198:199], 0, s[4:5]
	v_lshl_add_u64 v[200:201], v[200:201], 0, s[4:5]
	global_load_dwordx4 v[132:135], v[198:199], off
	global_load_dwordx4 v[136:139], v[200:201], off
	s_and_b64 vcc, exec, s[94:95]
	s_cbranch_vccnz .LBB0_1119
	s_mov_b64 s[4:5], 0x60000
	v_lshl_add_u64 v[50:51], v[198:199], 0, s[4:5]
	global_load_dwordx4 v[140:143], v[50:51], off
	v_lshl_add_u64 v[50:51], v[200:201], 0, s[4:5]
	global_load_dwordx4 v[144:147], v[50:51], off

; template <bool HAS_POST, class MaskF>
; __device__ __forceinline__ void attn_run(LAS unsigned char* lds, const bf16* Kg, const bf16* Vg, int pitch, int t0, int t1,
;                                          const bf16x8 (&qr)[4], f32x16& o0, f32x16& o1, f32x16& o2, MaskF& mf, const int wv) {
;     ...
;     for (int ts = t0; ts < t1; ts += 2) {
;         const int cur = ((ts - t0) >> 1) & 1;
;         const bool more = (ts + 2 < t1), more2 = (ts + 3 < t1);
;         if (more) { kp += 2 * tstride; kreg0 = *(const v4u*)kp; vp += 2 * tstride; vreg0 = *(const v4u*)vp;
;             if (more2) { kreg1 = *(const v4u*)(kp + tstride); vreg1 = *(const v4u*)(vp + tstride); } }
; #pragma unroll
;         for (int j = 0; j < 2; ++j) {
;             const int t = ts + j;
;             if (t >= t1) break;
;             if (mf.skip(t)) continue;
;     __device__ __forceinline__ bool skip(int t) const { const int nb = t >> 2; if (nb >= qb) return 64 * (t & 3) > wq0 + 31; return !__any((int)((sel >> nb) & 1u)); }
.LBB0_1166:
	s_add_i32 s1, s37, -1
	s_add_i32 s58, s37, 1
	s_cmp_lt_u32 s58, s35
	s_cselect_b64 s[4:5], -1, 0
	s_cmp_le_u32 s1, s34
	s_cselect_b64 s[6:7], -1, 0
	v_cndmask_b32_e64 v48, 0, 1, s[6:7]
	s_cmp_ge_u32 s58, s35
	v_cmp_ne_u32_e64 s[6:7], 1, v48
	s_cbranch_scc1 .LBB0_1170
	s_mov_b64 s[8:9], 0x100000
	v_lshl_add_u64 v[154:155], v[154:155], 0, s[8:9]
	v_lshl_add_u64 v[156:157], v[156:157], 0, s[8:9]
	global_load_dwordx4 v[96:99], v[154:155], off
	global_load_dwordx4 v[100:103], v[156:157], off
	s_and_b64 vcc, exec, s[6:7]
	s_cbranch_vccnz .LBB0_1169
	s_mov_b64 s[8:9], 0x80000
	v_lshl_add_u64 v[48:49], v[154:155], 0, s[8:9]
	global_load_dwordx4 v[104:107], v[48:49], off
	v_lshl_add_u64 v[48:49], v[156:157], 0, s[8:9]
	global_load_dwordx4 v[108:111], v[48:49], off
.LBB0_1169:
.LBB0_1170:
	s_lshr_b32 s60, s1, 2
	s_cmp_ge_u32 s60, s33
	s_cselect_b64 s[30:31], -1, 0
	s_cmp_lt_u32 s60, s33
	s_mov_b64 s[10:11], -1
	s_cbranch_scc1 .LBB0_1184
	s_sub_i32 s0, s36, 64
	s_and_b32 s0, s0, 0x80
	v_readlane_b32 s8, v254, 2
	s_cmp_gt_u32 s0, s8
	s_cselect_b64 s[8:9], -1, 0
	s_lshl_b32 s0, 1, s60
	s_cbranch_execz .LBB0_1185

; template <bool HAS_POST, class MaskF>
; __device__ __forceinline__ void attn_run(LAS unsigned char* lds, const bf16* Kg, const bf16* Vg, int pitch, int t0, int t1,
;                                          const bf16x8 (&qr)[4], f32x16& o0, f32x16& o1, f32x16& o2, MaskF& mf, const int wv) {
;     ...
;             if (wv < 4) __builtin_amdgcn_s_setprio(1);
.LBB0_1173:
	s_andn2_b64 s[8:9], exec, s[24:25]
	s_andn2_b64 vcc, exec, s[24:25]
	s_cbranch_vccnz .LBB0_1175
	s_setprio 1

; #define LAS __attribute__((address_space(3)))
; template <bool HAS_POST, class MaskF>
; __device__ __forceinline__ void attn_run(LAS unsigned char* lds, const bf16* Kg, const bf16* Vg, int pitch, int t0, int t1,
;                                          const bf16x8 (&qr)[4], f32x16& o0, f32x16& o1, f32x16& o2, MaskF& mf, const int wv) {
;     ...
;         for (int j = 0; j < 2; ++j) {
;             const int t = ts + j;
;             if (t >= t1) break;
;             if (mf.skip(t)) continue;
;             f32x16 p0, p1; const f32x16 zc = {};
;             LAS unsigned char* Kb = lds + (cur * 2 + j) * KBUF + cx.kroff;
;             if (wv < 4) __builtin_amdgcn_s_setprio(1);
;     __device__ __forceinline__ bool skip(int t) const { const int nb = t >> 2; if (nb >= qb) return 64 * (t & 3) > wq0 + 31; return !__any((int)((sel >> nb) & 1u)); }
.LBB0_1188:
	s_cmp_ge_u32 s37, s35
	s_cbranch_scc1 .LBB0_1204
	s_andn2_b64 s[8:9], exec, s[30:31]
	s_andn2_b64 vcc, exec, s[30:31]
	s_mov_b64 s[10:11], -1
	s_cbranch_vccnz .LBB0_1202
	s_and_b32 s1, s36, 0xc0
	v_readlane_b32 s12, v254, 2
	s_cmp_gt_u32 s1, s12
	s_cselect_b64 s[12:13], -1, 0
	v_and_b32_e32 v168, s0, v159
	v_cmp_ne_u32_e64 s[10:11], 0, v168
	s_cbranch_execz .LBB0_1203

; template <bool HAS_POST, class MaskF>
; __device__ __forceinline__ void attn_run(LAS unsigned char* lds, const bf16* Kg, const bf16* Vg, int pitch, int t0, int t1,
;                                          const bf16x8 (&qr)[4], f32x16& o0, f32x16& o1, f32x16& o2, MaskF& mf, const int wv) {
;     ...
;             if (wv < 4) __builtin_amdgcn_s_setprio(1);
.LBB0_1192:
	s_andn2_b64 s[10:11], exec, s[24:25]
	s_andn2_b64 vcc, exec, s[24:25]
	s_cbranch_vccnz .LBB0_1194
	s_setprio 1
